# attention softmax row-sum with packed f32 adds (v_pk_add_f32, 2 pairs per MFMA slot, non-deferred PV)
# speedup vs baseline: 1.0054x; 1.0054x over previous
; __device__ __forceinline__ unsigned cvt_pk_bf16(float lo, float hi) { unsigned r; asm volatile("v_cvt_pk_bf16_f32 %0, %1, %2" : "=v"(r) : "v"(lo), "v"(hi)); return r; }
; __device__ __forceinline__ void phase_attn(const Params& p, unsigned char* lds) {
;     ...
;             bf16x8 P[2][2];
; #pragma unroll
;             for (int kb = 0; kb < 2; ++kb)
; #pragma unroll
;                 for (int s2 = 0; s2 < 2; ++s2) { u32x4 pk;
; #pragma unroll
;                     for (int jj = 0; jj < 4; ++jj) { const float p0 = __builtin_amdgcn_exp2f(st[kb][8 * s2 + 2 * jj] - mnew), p1 = __builtin_amdgcn_exp2f(st[kb][8 * s2 + 2 * jj + 1] - mnew); lsum += p0 + p1; pk[jj] = cvt_pk_bf16(p0, p1); }
;                     P[kb][s2] = __builtin_bit_cast(bf16x8, pk); }
.Lat_norescale_1:
	v_mov_b32_e32 v236, 0
	v_mov_b32_e32 v237, 0
	s_waitcnt lgkmcnt(7)
	v_mfma_f32_32x32x16_bf16 v[196:211], v[172:175], v[108:111], 0
	v_sub_f32_e32 v80, v80, v149
	v_sub_f32_e32 v81, v81, v149
	v_sub_f32_e32 v82, v82, v149
	v_sub_f32_e32 v83, v83, v149
	v_exp_f32_e32 v80, v80
	v_exp_f32_e32 v81, v81
	v_exp_f32_e32 v82, v82
	v_exp_f32_e32 v83, v83
	v_pk_add_f32 v[236:237], v[236:237], v[80:81]
	v_cvt_pk_bf16_f32 v80, v80, v81
	v_pk_add_f32 v[236:237], v[236:237], v[82:83]
	v_cvt_pk_bf16_f32 v81, v82, v83
	s_waitcnt lgkmcnt(6)
	v_mfma_f32_32x32x16_bf16 v[196:211], v[176:179], v[104:107], v[196:211]
	v_sub_f32_e32 v84, v84, v149
	v_sub_f32_e32 v85, v85, v149
	v_sub_f32_e32 v86, v86, v149
	v_sub_f32_e32 v87, v87, v149
	v_exp_f32_e32 v84, v84
	v_exp_f32_e32 v85, v85
	v_exp_f32_e32 v86, v86
	v_exp_f32_e32 v87, v87
	v_pk_add_f32 v[236:237], v[236:237], v[84:85]
	v_cvt_pk_bf16_f32 v82, v84, v85
	v_pk_add_f32 v[236:237], v[236:237], v[86:87]
	v_cvt_pk_bf16_f32 v83, v86, v87
	s_waitcnt lgkmcnt(5)
	v_mfma_f32_32x32x16_bf16 v[196:211], v[180:183], v[100:103], v[196:211]
	v_sub_f32_e32 v88, v88, v149
	v_sub_f32_e32 v89, v89, v149
	v_sub_f32_e32 v90, v90, v149
	v_sub_f32_e32 v91, v91, v149
	v_exp_f32_e32 v88, v88
	v_exp_f32_e32 v89, v89
	v_exp_f32_e32 v90, v90
	v_exp_f32_e32 v91, v91
	v_pk_add_f32 v[236:237], v[236:237], v[88:89]
	v_cvt_pk_bf16_f32 v84, v88, v89
	v_pk_add_f32 v[236:237], v[236:237], v[90:91]
	v_cvt_pk_bf16_f32 v85, v90, v91
	s_waitcnt lgkmcnt(4)
	v_mfma_f32_32x32x16_bf16 v[196:211], v[184:187], v[96:99], v[196:211]
	ds_read_b128 v[172:175], v159 offset:34816
	ds_read_b128 v[176:179], v159 offset:34848
	ds_read_b128 v[180:183], v159 offset:34880
	ds_read_b128 v[184:187], v159 offset:34912
	v_sub_f32_e32 v92, v92, v149
	v_sub_f32_e32 v93, v93, v149
	v_sub_f32_e32 v94, v94, v149
	v_sub_f32_e32 v95, v95, v149
	v_exp_f32_e32 v92, v92
	v_exp_f32_e32 v93, v93
	v_exp_f32_e32 v94, v94
	v_exp_f32_e32 v95, v95
	v_pk_add_f32 v[236:237], v[236:237], v[92:93]
	v_cvt_pk_bf16_f32 v86, v92, v93
	v_pk_add_f32 v[236:237], v[236:237], v[94:95]
	v_cvt_pk_bf16_f32 v87, v94, v95
	s_waitcnt lgkmcnt(7)
	v_mfma_f32_32x32x16_bf16 v[212:227], v[188:191], v[108:111], 0
	v_sub_f32_e32 v64, v64, v149
	v_sub_f32_e32 v65, v65, v149
	v_sub_f32_e32 v66, v66, v149
	v_sub_f32_e32 v67, v67, v149
	v_exp_f32_e32 v64, v64
	v_exp_f32_e32 v65, v65
	v_exp_f32_e32 v66, v66
	v_exp_f32_e32 v67, v67
	v_pk_add_f32 v[236:237], v[236:237], v[64:65]
	v_cvt_pk_bf16_f32 v64, v64, v65
	v_pk_add_f32 v[236:237], v[236:237], v[66:67]
	v_cvt_pk_bf16_f32 v65, v66, v67
	s_waitcnt lgkmcnt(6)
	v_mfma_f32_32x32x16_bf16 v[212:227], v[192:195], v[104:107], v[212:227]
	v_sub_f32_e32 v68, v68, v149
	v_sub_f32_e32 v69, v69, v149
	v_sub_f32_e32 v70, v70, v149
	v_sub_f32_e32 v71, v71, v149
	v_exp_f32_e32 v68, v68
	v_exp_f32_e32 v69, v69
	v_exp_f32_e32 v70, v70
	v_exp_f32_e32 v71, v71
	v_pk_add_f32 v[236:237], v[236:237], v[68:69]
	v_cvt_pk_bf16_f32 v66, v68, v69
	v_pk_add_f32 v[236:237], v[236:237], v[70:71]
	v_cvt_pk_bf16_f32 v67, v70, v71
	s_waitcnt lgkmcnt(5)
	v_mfma_f32_32x32x16_bf16 v[212:227], v[228:231], v[100:103], v[212:227]
	v_sub_f32_e32 v72, v72, v149
	v_sub_f32_e32 v73, v73, v149
	v_sub_f32_e32 v74, v74, v149
	v_sub_f32_e32 v75, v75, v149
	v_exp_f32_e32 v72, v72
	v_exp_f32_e32 v73, v73
	v_exp_f32_e32 v74, v74
	v_exp_f32_e32 v75, v75
	v_pk_add_f32 v[236:237], v[236:237], v[72:73]
	v_cvt_pk_bf16_f32 v68, v72, v73
	v_pk_add_f32 v[236:237], v[236:237], v[74:75]
	v_cvt_pk_bf16_f32 v69, v74, v75
	s_waitcnt lgkmcnt(4)
; __device__ __forceinline__ unsigned cvt_pk_bf16(float lo, float hi) { unsigned r; asm volatile("v_cvt_pk_bf16_f32 %0, %1, %2" : "=v"(r) : "v"(lo), "v"(hi)); return r; }
; __device__ __forceinline__ void phase_attn(const Params& p, unsigned char* lds) {
;     ...
;             float mloc = st[0][0];
; #pragma unroll
;             for (int i = 0; i < 16; ++i) { mloc = fmaxf(mloc, st[0][i]); mloc = fmaxf(mloc, st[1][i]); }
;             mloc = fmaxf(mloc, __shfl_xor(mloc, 32));
;             const float mnew = fmaxf(mrun, mloc);
;             if (__builtin_amdgcn_ballot_w64(mnew > mrun) != 0ull) {
;                 const float alpha = __builtin_amdgcn_exp2f(mrun - mnew);
;                 lsum *= alpha;
; #pragma unroll
;                 for (int vb = 0; vb < 4; ++vb)
; #pragma unroll
;                     for (int i = 0; i < 16; ++i) ot[vb][i] *= alpha;
;             }
;             mrun = mnew;
;             bf16x8 P[2][2];
; #pragma unroll
;             for (int kb = 0; kb < 2; ++kb)
; #pragma unroll
;                 for (int s2 = 0; s2 < 2; ++s2) { u32x4 pk;
; #pragma unroll
;                     for (int jj = 0; jj < 4; ++jj) { const float p0 = __builtin_amdgcn_exp2f(st[kb][8 * s2 + 2 * jj] - mnew), p1 = __builtin_amdgcn_exp2f(st[kb][8 * s2 + 2 * jj + 1] - mnew); lsum += p0 + p1; pk[jj] = cvt_pk_bf16(p0, p1); }
;                     P[kb][s2] = __builtin_bit_cast(bf16x8, pk); }
;             {
;                 bf16x8 vf[2][4];
;     ...
;                 AT_LDV(0, 0);
; #pragma unroll
;                 for (int vb = 0; vb < 4; ++vb) {
;                     if (vb < 3) AT_LDV((vb + 1) & 1, vb + 1);
;                     __builtin_amdgcn_sched_barrier(0);
;                     __builtin_amdgcn_s_setprio(2);
; #pragma unroll
;                     for (int kb = 0; kb < 2; ++kb)
; #pragma unroll
;                         for (int s2 = 0; s2 < 2; ++s2) ot[vb] = __builtin_amdgcn_mfma_f32_32x32x16_bf16(vf[vb & 1][kb * 2 + s2], P[kb][s2], ot[vb], 0, 0, 0);
;                     __builtin_amdgcn_s_setprio(0);
;                     __builtin_amdgcn_sched_barrier(0);
;                 }
;     ...
;             }
;             if (kt + 1 < 64) { AT_STOREK(buf ^ 1); AT_STOREV(buf ^ 1); }
	v_mfma_f32_32x32x16_bf16 v[212:227], v[232:235], v[96:99], v[212:227]
	ds_read_b128 v[188:191], v159 offset:39424
	ds_read_b128 v[192:195], v159 offset:39456
	ds_read_b128 v[228:231], v159 offset:39488
	ds_read_b128 v[232:235], v159 offset:39520
	v_sub_f32_e32 v76, v76, v149
	v_sub_f32_e32 v77, v77, v149
	v_sub_f32_e32 v78, v78, v149
	v_sub_f32_e32 v79, v79, v149
	v_exp_f32_e32 v76, v76
	v_exp_f32_e32 v77, v77
	v_exp_f32_e32 v78, v78
	v_exp_f32_e32 v79, v79
	v_pk_add_f32 v[236:237], v[236:237], v[76:77]
	v_cvt_pk_bf16_f32 v70, v76, v77
	v_pk_add_f32 v[236:237], v[236:237], v[78:79]
	v_cvt_pk_bf16_f32 v71, v78, v79
	v_add_f32_e32 v128, v128, v236
	v_add_f32_e32 v128, v128, v237
	s_waitcnt lgkmcnt(7)
	v_mfma_f32_32x32x16_bf16 v[48:63], v[172:175], v[80:83], v[48:63]
	s_waitcnt lgkmcnt(6)
	v_mfma_f32_32x32x16_bf16 v[48:63], v[176:179], v[84:87], v[48:63]
	v_max3_f32 v145, v196, v197, v198
	v_max3_f32 v237, v212, v213, v214
	v_max3_f32 v145, v145, v199, v200
	s_waitcnt lgkmcnt(5)
	v_mfma_f32_32x32x16_bf16 v[48:63], v[180:183], v[64:67], v[48:63]
	v_max3_f32 v237, v237, v215, v216
	v_max3_f32 v145, v145, v201, v202
	v_max3_f32 v237, v237, v217, v218
	s_waitcnt lgkmcnt(4)
	v_mfma_f32_32x32x16_bf16 v[48:63], v[184:187], v[68:71], v[48:63]
	v_max3_f32 v145, v145, v203, v204
	v_max3_f32 v237, v237, v219, v220
	v_max3_f32 v145, v145, v205, v206
	ds_read_b128 v[172:175], v159 offset:44032
	ds_read_b128 v[176:179], v159 offset:44064
	ds_read_b128 v[180:183], v159 offset:44096
	ds_read_b128 v[184:187], v159 offset:44128
	s_waitcnt lgkmcnt(7)
	v_mfma_f32_32x32x16_bf16 v[32:47], v[188:191], v[80:83], v[32:47]
	v_max3_f32 v237, v237, v221, v222
	v_max3_f32 v145, v145, v207, v208
	v_max3_f32 v237, v237, v223, v224
	s_waitcnt lgkmcnt(6)
	v_mfma_f32_32x32x16_bf16 v[32:47], v[192:195], v[84:87], v[32:47]
	v_max3_f32 v145, v145, v209, v210
	v_max3_f32 v237, v237, v225, v226
	v_max_f32_e32 v145, v145, v211
	s_waitcnt lgkmcnt(5)
	v_mfma_f32_32x32x16_bf16 v[32:47], v[228:231], v[64:67], v[32:47]
	v_max_f32_e32 v237, v237, v227
	v_max_f32_e32 v145, v145, v237
	ds_bpermute_b32 v237, v158, v145
	s_waitcnt lgkmcnt(5)
	v_mfma_f32_32x32x16_bf16 v[32:47], v[232:235], v[68:71], v[32:47]
	v_add_u32_e32 v239, v131, v164
	s_waitcnt vmcnt(3)
	ds_write_b128 v239, v[116:119] offset:0
	ds_read_b128 v[188:191], v159 offset:48640
	ds_read_b128 v[192:195], v159 offset:48672
	ds_read_b128 v[228:231], v159 offset:48704
	ds_read_b128 v[232:235], v159 offset:48736
	s_waitcnt lgkmcnt(9)
	v_mfma_f32_32x32x16_bf16 v[16:31], v[172:175], v[80:83], v[16:31]
	v_add_u32_e32 v239, v131, v165
	s_waitcnt vmcnt(2)
	ds_write_b128 v239, v[112:115] offset:0
	s_waitcnt lgkmcnt(9)
	v_mfma_f32_32x32x16_bf16 v[16:31], v[176:179], v[84:87], v[16:31]
	v_add_u32_e32 v239, v156, v166
	s_waitcnt vmcnt(1)
	ds_write_b128 v239, v[124:127] offset:53248
	s_waitcnt lgkmcnt(9)
	v_mfma_f32_32x32x16_bf16 v[16:31], v[180:183], v[64:67], v[16:31]
	v_add_u32_e32 v239, v156, v167
	s_waitcnt vmcnt(0)
	ds_write_b128 v239, v[120:123] offset:53248
	s_waitcnt lgkmcnt(9)
	v_mfma_f32_32x32x16_bf16 v[16:31], v[184:187], v[68:71], v[16:31]
	s_waitcnt lgkmcnt(8)
	v_max_f32_e32 v237, v145, v237
	v_add_f32_e32 v239, 0x41000000, v149
	v_max_f32_e32 v145, v149, v237
	s_waitcnt lgkmcnt(6)
	v_mfma_f32_32x32x16_bf16 v[0:15], v[188:191], v[80:83], v[0:15]
	v_sub_f32_e32 v238, v149, v145
	v_cmp_gt_f32_e32 vcc, v237, v239
	v_exp_f32_e32 v238, v238
	s_waitcnt lgkmcnt(5)
	v_mfma_f32_32x32x16_bf16 v[0:15], v[192:195], v[84:87], v[0:15]
	s_waitcnt lgkmcnt(4)
	v_mfma_f32_32x32x16_bf16 v[0:15], v[228:231], v[64:67], v[0:15]
	s_waitcnt lgkmcnt(3)
	v_mfma_f32_32x32x16_bf16 v[0:15], v[232:235], v[68:71], v[0:15]
	s_cbranch_vccz .Lat_keepm_2
	v_mov_b32_e32 v149, v145

; __device__ __forceinline__ unsigned cvt_pk_bf16(float lo, float hi) { unsigned r; asm volatile("v_cvt_pk_bf16_f32 %0, %1, %2" : "=v"(r) : "v"(lo), "v"(hi)); return r; }
; #define AT_LOADK(kt) do { _Pragma("unroll") for (int i_ = 0; i_ < 2; ++i_) { const int id_ = tid + 512 * i_; \
;             kr[i_] = *(const u32x4*)(kbase + (size_t)((kt) * 64 + (id_ >> 4)) * 4096 + (id_ & 15) * 8); } } while (0)
; #define AT_LOADV(kt) do { _Pragma("unroll") for (int i_ = 0; i_ < 2; ++i_) { const int id_ = tid + 512 * i_; \
;             vr[i_] = *(const u32x4*)(vbase + (size_t)(id_ >> 3) * 4096 + (kt) * 64 + (id_ & 7) * 8); } } while (0)
; __device__ __forceinline__ void phase_attn(const Params& p, unsigned char* lds) {
;     ...
;         for (int kt = 0; kt < 64; ++kt) {
;             const int buf = kt & 1;
;             if (kt + 1 < 64) { AT_LOADK((kt + 1 + toff) & 63); AT_LOADV((kt + 1 + toff) & 63); }
;             AT_QK(st, buf);
;             float mloc = st[0][0];
; #pragma unroll
;             for (int i = 0; i < 16; ++i) { mloc = fmaxf(mloc, st[0][i]); mloc = fmaxf(mloc, st[1][i]); }
;             mloc = fmaxf(mloc, __shfl_xor(mloc, 32));
;             const float mnew = fmaxf(mrun, mloc);
;             if (__builtin_amdgcn_ballot_w64(mnew > mrun) != 0ull) {
;                 const float alpha = __builtin_amdgcn_exp2f(mrun - mnew);
;                 lsum *= alpha;
; #pragma unroll
;                 for (int vb = 0; vb < 4; ++vb)
; #pragma unroll
;                     for (int i = 0; i < 16; ++i) ot[vb][i] *= alpha;
;             }
;             mrun = mnew;
;             bf16x8 P[2][2];
; #pragma unroll
;             for (int kb = 0; kb < 2; ++kb)
; #pragma unroll
;                 for (int s2 = 0; s2 < 2; ++s2) { u32x4 pk;
; #pragma unroll
;                     for (int jj = 0; jj < 4; ++jj) { const float p0 = __builtin_amdgcn_exp2f(st[kb][8 * s2 + 2 * jj] - mnew), p1 = __builtin_amdgcn_exp2f(st[kb][8 * s2 + 2 * jj + 1] - mnew); lsum += p0 + p1; pk[jj] = cvt_pk_bf16(p0, p1); }
;                     P[kb][s2] = __builtin_bit_cast(bf16x8, pk); }
.Lat_loop:
	ds_read_b128 v[172:175], v157 offset:0
	ds_read_b128 v[176:179], v157 offset:32
	ds_read_b128 v[180:183], v157 offset:64
	ds_read_b128 v[184:187], v157 offset:96
	ds_read_b128 v[188:191], v157 offset:8704
	ds_read_b128 v[192:195], v157 offset:8736
	ds_read_b128 v[228:231], v157 offset:8768
	ds_read_b128 v[232:235], v157 offset:8800
	s_add_i32 s12, s21, 64
	s_and_b32 s12, s12, 0xfc0
	v_add_u32_e32 v116, s12, v162
	v_ashrrev_i32_e32 v117, 31, v116
	v_add_u32_e32 v112, s12, v163
	v_lshlrev_b64 v[116:117], 13, v[116:117]
	v_ashrrev_i32_e32 v113, 31, v112
	v_lshl_add_u64 v[116:117], v[152:153], 0, v[116:117]
	v_lshlrev_b64 v[112:113], 13, v[112:113]
	v_lshl_add_u64 v[112:113], v[152:153], 0, v[112:113]
	global_load_dwordx4 v[116:119], v[116:117], off
	global_load_dwordx4 v[112:115], v[112:113], off
	s_and_b32 s12, s21, 0xfc0
	s_lshl_b32 s12, s12, 1
	v_lshl_add_u64 v[124:125], v[154:155], 0, s[12:13]
	v_lshl_add_u64 v[120:121], v[124:125], 0, v[138:139]
	v_lshl_add_u64 v[124:125], v[124:125], 0, v[136:137]
	global_load_dwordx4 v[124:127], v[124:125], off
	global_load_dwordx4 v[120:123], v[120:121], off
	s_cbranch_vccz .Lat_norescale_3
	v_pk_mul_f32 v[62:63], v[62:63], v[238:239] op_sel_hi:[1,0]
	v_pk_mul_f32 v[60:61], v[60:61], v[238:239] op_sel_hi:[1,0]
	v_pk_mul_f32 v[58:59], v[58:59], v[238:239] op_sel_hi:[1,0]
	v_pk_mul_f32 v[56:57], v[56:57], v[238:239] op_sel_hi:[1,0]
	v_pk_mul_f32 v[54:55], v[54:55], v[238:239] op_sel_hi:[1,0]
	v_pk_mul_f32 v[52:53], v[52:53], v[238:239] op_sel_hi:[1,0]
	v_pk_mul_f32 v[50:51], v[50:51], v[238:239] op_sel_hi:[1,0]
	v_pk_mul_f32 v[48:49], v[48:49], v[238:239] op_sel_hi:[1,0]
	v_pk_mul_f32 v[46:47], v[46:47], v[238:239] op_sel_hi:[1,0]
	v_pk_mul_f32 v[44:45], v[44:45], v[238:239] op_sel_hi:[1,0]
	v_pk_mul_f32 v[42:43], v[42:43], v[238:239] op_sel_hi:[1,0]
	v_pk_mul_f32 v[40:41], v[40:41], v[238:239] op_sel_hi:[1,0]
	v_pk_mul_f32 v[38:39], v[38:39], v[238:239] op_sel_hi:[1,0]
	v_pk_mul_f32 v[36:37], v[36:37], v[238:239] op_sel_hi:[1,0]
	v_pk_mul_f32 v[34:35], v[34:35], v[238:239] op_sel_hi:[1,0]
	v_pk_mul_f32 v[32:33], v[32:33], v[238:239] op_sel_hi:[1,0]
	v_pk_mul_f32 v[30:31], v[30:31], v[238:239] op_sel_hi:[1,0]
	v_pk_mul_f32 v[28:29], v[28:29], v[238:239] op_sel_hi:[1,0]
	v_pk_mul_f32 v[26:27], v[26:27], v[238:239] op_sel_hi:[1,0]
	v_pk_mul_f32 v[24:25], v[24:25], v[238:239] op_sel_hi:[1,0]
	v_pk_mul_f32 v[22:23], v[22:23], v[238:239] op_sel_hi:[1,0]
	v_pk_mul_f32 v[20:21], v[20:21], v[238:239] op_sel_hi:[1,0]
	v_pk_mul_f32 v[18:19], v[18:19], v[238:239] op_sel_hi:[1,0]
	v_pk_mul_f32 v[16:17], v[16:17], v[238:239] op_sel_hi:[1,0]
	v_pk_mul_f32 v[14:15], v[14:15], v[238:239] op_sel_hi:[1,0]
	v_pk_mul_f32 v[12:13], v[12:13], v[238:239] op_sel_hi:[1,0]
	v_pk_mul_f32 v[10:11], v[10:11], v[238:239] op_sel_hi:[1,0]
	v_pk_mul_f32 v[8:9], v[8:9], v[238:239] op_sel_hi:[1,0]
	v_pk_mul_f32 v[6:7], v[6:7], v[238:239] op_sel_hi:[1,0]
	v_pk_mul_f32 v[4:5], v[4:5], v[238:239] op_sel_hi:[1,0]
	v_pk_mul_f32 v[2:3], v[2:3], v[238:239] op_sel_hi:[1,0]
	v_pk_mul_f32 v[0:1], v[0:1], v[238:239] op_sel_hi:[1,0]
	v_mul_f32_e32 v128, v128, v238
.Lat_norescale_3:
	v_mov_b32_e32 v236, 0
	v_mov_b32_e32 v237, 0
	s_waitcnt lgkmcnt(7)
	v_mfma_f32_32x32x16_bf16 v[80:95], v[172:175], v[108:111], 0
	v_sub_f32_e32 v196, v196, v149
	v_sub_f32_e32 v197, v197, v149
	v_sub_f32_e32 v198, v198, v149
	v_sub_f32_e32 v199, v199, v149
	v_exp_f32_e32 v196, v196
	v_exp_f32_e32 v197, v197
	v_exp_f32_e32 v198, v198
	v_exp_f32_e32 v199, v199
	v_pk_add_f32 v[236:237], v[236:237], v[196:197]
	v_cvt_pk_bf16_f32 v196, v196, v197
	v_pk_add_f32 v[236:237], v[236:237], v[198:199]
	v_cvt_pk_bf16_f32 v197, v198, v199
	s_waitcnt lgkmcnt(6)
	v_mfma_f32_32x32x16_bf16 v[80:95], v[176:179], v[104:107], v[80:95]
	v_sub_f32_e32 v200, v200, v149
	v_sub_f32_e32 v201, v201, v149
	v_sub_f32_e32 v202, v202, v149
	v_sub_f32_e32 v203, v203, v149
	v_exp_f32_e32 v200, v200
	v_exp_f32_e32 v201, v201
	v_exp_f32_e32 v202, v202
	v_exp_f32_e32 v203, v203
	v_pk_add_f32 v[236:237], v[236:237], v[200:201]
	v_cvt_pk_bf16_f32 v198, v200, v201
	v_pk_add_f32 v[236:237], v[236:237], v[202:203]
	v_cvt_pk_bf16_f32 v199, v202, v203
	s_waitcnt lgkmcnt(5)
	v_mfma_f32_32x32x16_bf16 v[80:95], v[180:183], v[100:103], v[80:95]
	v_sub_f32_e32 v204, v204, v149
	v_sub_f32_e32 v205, v205, v149
	v_sub_f32_e32 v206, v206, v149
	v_sub_f32_e32 v207, v207, v149
	v_exp_f32_e32 v204, v204
	v_exp_f32_e32 v205, v205
	v_exp_f32_e32 v206, v206
	v_exp_f32_e32 v207, v207
	v_pk_add_f32 v[236:237], v[236:237], v[204:205]
	v_cvt_pk_bf16_f32 v200, v204, v205
	v_pk_add_f32 v[236:237], v[236:237], v[206:207]
	v_cvt_pk_bf16_f32 v201, v206, v207
	s_waitcnt lgkmcnt(4)
	v_mfma_f32_32x32x16_bf16 v[80:95], v[184:187], v[96:99], v[80:95]
	ds_read_b128 v[172:175], v147 offset:34816
	ds_read_b128 v[176:179], v147 offset:34848
	ds_read_b128 v[180:183], v147 offset:34880
	ds_read_b128 v[184:187], v147 offset:34912
	v_sub_f32_e32 v208, v208, v149
	v_sub_f32_e32 v209, v209, v149
	v_sub_f32_e32 v210, v210, v149
	v_sub_f32_e32 v211, v211, v149
	v_exp_f32_e32 v208, v208
	v_exp_f32_e32 v209, v209
	v_exp_f32_e32 v210, v210
	v_exp_f32_e32 v211, v211
	v_pk_add_f32 v[236:237], v[236:237], v[208:209]
	v_cvt_pk_bf16_f32 v202, v208, v209
	v_pk_add_f32 v[236:237], v[236:237], v[210:211]
	v_cvt_pk_bf16_f32 v203, v210, v211
	s_waitcnt lgkmcnt(7)
	v_mfma_f32_32x32x16_bf16 v[64:79], v[188:191], v[108:111], 0
	v_sub_f32_e32 v212, v212, v149
	v_sub_f32_e32 v213, v213, v149
	v_sub_f32_e32 v214, v214, v149
	v_sub_f32_e32 v215, v215, v149
	v_exp_f32_e32 v212, v212
	v_exp_f32_e32 v213, v213
	v_exp_f32_e32 v214, v214
	v_exp_f32_e32 v215, v215
	v_pk_add_f32 v[236:237], v[236:237], v[212:213]
	v_cvt_pk_bf16_f32 v212, v212, v213
	v_pk_add_f32 v[236:237], v[236:237], v[214:215]
	v_cvt_pk_bf16_f32 v213, v214, v215
	s_waitcnt lgkmcnt(6)
; __device__ __forceinline__ unsigned cvt_pk_bf16(float lo, float hi) { unsigned r; asm volatile("v_cvt_pk_bf16_f32 %0, %1, %2" : "=v"(r) : "v"(lo), "v"(hi)); return r; }
; __device__ __forceinline__ void phase_attn(const Params& p, unsigned char* lds) {
;     ...
;             float mloc = st[0][0];
; #pragma unroll
;             for (int i = 0; i < 16; ++i) { mloc = fmaxf(mloc, st[0][i]); mloc = fmaxf(mloc, st[1][i]); }
;             mloc = fmaxf(mloc, __shfl_xor(mloc, 32));
;             const float mnew = fmaxf(mrun, mloc);
;             if (__builtin_amdgcn_ballot_w64(mnew > mrun) != 0ull) {
;                 const float alpha = __builtin_amdgcn_exp2f(mrun - mnew);
;                 lsum *= alpha;
; #pragma unroll
;                 for (int vb = 0; vb < 4; ++vb)
; #pragma unroll
;                     for (int i = 0; i < 16; ++i) ot[vb][i] *= alpha;
;             }
;             mrun = mnew;
;             bf16x8 P[2][2];
; #pragma unroll
;             for (int kb = 0; kb < 2; ++kb)
; #pragma unroll
;                 for (int s2 = 0; s2 < 2; ++s2) { u32x4 pk;
; #pragma unroll
;                     for (int jj = 0; jj < 4; ++jj) { const float p0 = __builtin_amdgcn_exp2f(st[kb][8 * s2 + 2 * jj] - mnew), p1 = __builtin_amdgcn_exp2f(st[kb][8 * s2 + 2 * jj + 1] - mnew); lsum += p0 + p1; pk[jj] = cvt_pk_bf16(p0, p1); }
;                     P[kb][s2] = __builtin_bit_cast(bf16x8, pk); }
;             {
;                 bf16x8 vf[2][4];
;     ...
;                 AT_LDV(0, 0);
; #pragma unroll
;                 for (int vb = 0; vb < 4; ++vb) {
;                     if (vb < 3) AT_LDV((vb + 1) & 1, vb + 1);
;                     __builtin_amdgcn_sched_barrier(0);
;                     __builtin_amdgcn_s_setprio(2);
; #pragma unroll
;                     for (int kb = 0; kb < 2; ++kb)
; #pragma unroll
;                         for (int s2 = 0; s2 < 2; ++s2) ot[vb] = __builtin_amdgcn_mfma_f32_32x32x16_bf16(vf[vb & 1][kb * 2 + s2], P[kb][s2], ot[vb], 0, 0, 0);
;                     __builtin_amdgcn_s_setprio(0);
;                     __builtin_amdgcn_sched_barrier(0);
;                 }
;     ...
;             }
;             if (kt + 1 < 64) { AT_STOREK(buf ^ 1); AT_STOREV(buf ^ 1); }
	v_mfma_f32_32x32x16_bf16 v[64:79], v[192:195], v[104:107], v[64:79]
	v_sub_f32_e32 v216, v216, v149
	v_sub_f32_e32 v217, v217, v149
	v_sub_f32_e32 v218, v218, v149
	v_sub_f32_e32 v219, v219, v149
	v_exp_f32_e32 v216, v216
	v_exp_f32_e32 v217, v217
	v_exp_f32_e32 v218, v218
	v_exp_f32_e32 v219, v219
	v_pk_add_f32 v[236:237], v[236:237], v[216:217]
	v_cvt_pk_bf16_f32 v214, v216, v217
	v_pk_add_f32 v[236:237], v[236:237], v[218:219]
	v_cvt_pk_bf16_f32 v215, v218, v219
	s_waitcnt lgkmcnt(5)
	v_mfma_f32_32x32x16_bf16 v[64:79], v[228:231], v[100:103], v[64:79]
	v_sub_f32_e32 v220, v220, v149
	v_sub_f32_e32 v221, v221, v149
	v_sub_f32_e32 v222, v222, v149
	v_sub_f32_e32 v223, v223, v149
	v_exp_f32_e32 v220, v220
	v_exp_f32_e32 v221, v221
	v_exp_f32_e32 v222, v222
	v_exp_f32_e32 v223, v223
	v_pk_add_f32 v[236:237], v[236:237], v[220:221]
	v_cvt_pk_bf16_f32 v216, v220, v221
	v_pk_add_f32 v[236:237], v[236:237], v[222:223]
	v_cvt_pk_bf16_f32 v217, v222, v223
	s_waitcnt lgkmcnt(4)
	v_mfma_f32_32x32x16_bf16 v[64:79], v[232:235], v[96:99], v[64:79]
	ds_read_b128 v[188:191], v147 offset:39424
	ds_read_b128 v[192:195], v147 offset:39456
	ds_read_b128 v[228:231], v147 offset:39488
	ds_read_b128 v[232:235], v147 offset:39520
	v_sub_f32_e32 v224, v224, v149
	v_sub_f32_e32 v225, v225, v149
	v_sub_f32_e32 v226, v226, v149
	v_sub_f32_e32 v227, v227, v149
	v_exp_f32_e32 v224, v224
	v_exp_f32_e32 v225, v225
	v_exp_f32_e32 v226, v226
	v_exp_f32_e32 v227, v227
	v_pk_add_f32 v[236:237], v[236:237], v[224:225]
	v_cvt_pk_bf16_f32 v218, v224, v225
	v_pk_add_f32 v[236:237], v[236:237], v[226:227]
	v_cvt_pk_bf16_f32 v219, v226, v227
	v_add_f32_e32 v128, v128, v236
	v_add_f32_e32 v128, v128, v237
	s_waitcnt lgkmcnt(7)
	v_mfma_f32_32x32x16_bf16 v[48:63], v[172:175], v[196:199], v[48:63]
	s_waitcnt lgkmcnt(6)
	v_mfma_f32_32x32x16_bf16 v[48:63], v[176:179], v[200:203], v[48:63]
	v_max3_f32 v145, v80, v81, v82
	v_max3_f32 v237, v64, v65, v66
	v_max3_f32 v145, v145, v83, v84
	s_waitcnt lgkmcnt(5)
	v_mfma_f32_32x32x16_bf16 v[48:63], v[180:183], v[212:215], v[48:63]
	v_max3_f32 v237, v237, v67, v68
	v_max3_f32 v145, v145, v85, v86
	v_max3_f32 v237, v237, v69, v70
	s_waitcnt lgkmcnt(4)
	v_mfma_f32_32x32x16_bf16 v[48:63], v[184:187], v[216:219], v[48:63]
	v_max3_f32 v145, v145, v87, v88
	v_max3_f32 v237, v237, v71, v72
	v_max3_f32 v145, v145, v89, v90
	ds_read_b128 v[172:175], v147 offset:44032
	ds_read_b128 v[176:179], v147 offset:44064
	ds_read_b128 v[180:183], v147 offset:44096
	ds_read_b128 v[184:187], v147 offset:44128
	s_waitcnt lgkmcnt(7)
	v_mfma_f32_32x32x16_bf16 v[32:47], v[188:191], v[196:199], v[32:47]
	v_max3_f32 v237, v237, v73, v74
	v_max3_f32 v145, v145, v91, v92
	v_max3_f32 v237, v237, v75, v76
	s_waitcnt lgkmcnt(6)
	v_mfma_f32_32x32x16_bf16 v[32:47], v[192:195], v[200:203], v[32:47]
	v_max3_f32 v145, v145, v93, v94
	v_max3_f32 v237, v237, v77, v78
	v_max_f32_e32 v145, v145, v95
	s_waitcnt lgkmcnt(5)
	v_mfma_f32_32x32x16_bf16 v[32:47], v[228:231], v[212:215], v[32:47]
	v_max_f32_e32 v237, v237, v79
	v_max_f32_e32 v145, v145, v237
	ds_bpermute_b32 v237, v158, v145
	s_waitcnt lgkmcnt(5)
	v_mfma_f32_32x32x16_bf16 v[32:47], v[232:235], v[216:219], v[32:47]
	v_add_u32_e32 v239, v131, v164
	s_waitcnt vmcnt(3)
	ds_write_b128 v239, v[116:119] offset:17408
	ds_read_b128 v[188:191], v147 offset:48640
	ds_read_b128 v[192:195], v147 offset:48672
	ds_read_b128 v[228:231], v147 offset:48704
	ds_read_b128 v[232:235], v147 offset:48736
	s_waitcnt lgkmcnt(9)
	v_mfma_f32_32x32x16_bf16 v[16:31], v[172:175], v[196:199], v[16:31]
	v_add_u32_e32 v239, v131, v165
	s_waitcnt vmcnt(2)
	ds_write_b128 v239, v[112:115] offset:17408
	s_waitcnt lgkmcnt(9)
	v_mfma_f32_32x32x16_bf16 v[16:31], v[176:179], v[200:203], v[16:31]
	v_add_u32_e32 v239, v156, v166
	s_waitcnt vmcnt(1)
	ds_write_b128 v239, v[124:127] offset:34816
	s_waitcnt lgkmcnt(9)
	v_mfma_f32_32x32x16_bf16 v[16:31], v[180:183], v[212:215], v[16:31]
	v_add_u32_e32 v239, v156, v167
	s_waitcnt vmcnt(0)
	ds_write_b128 v239, v[120:123] offset:34816
	s_waitcnt lgkmcnt(9)
	v_mfma_f32_32x32x16_bf16 v[16:31], v[184:187], v[216:219], v[16:31]
	s_waitcnt lgkmcnt(8)
	v_max_f32_e32 v237, v145, v237
	v_add_f32_e32 v239, 0x41000000, v149
	v_max_f32_e32 v145, v149, v237
	s_waitcnt lgkmcnt(6)
	v_mfma_f32_32x32x16_bf16 v[0:15], v[188:191], v[196:199], v[0:15]
	v_sub_f32_e32 v238, v149, v145
	v_cmp_gt_f32_e32 vcc, v237, v239
	v_exp_f32_e32 v238, v238
	s_waitcnt lgkmcnt(5)
	v_mfma_f32_32x32x16_bf16 v[0:15], v[192:195], v[200:203], v[0:15]
	s_waitcnt lgkmcnt(4)
	v_mfma_f32_32x32x16_bf16 v[0:15], v[228:231], v[212:215], v[0:15]
	s_waitcnt lgkmcnt(3)
	v_mfma_f32_32x32x16_bf16 v[0:15], v[232:235], v[216:219], v[0:15]
	s_cbranch_vccz .Lat_keepm_4
	v_mov_b32_e32 v149, v145
; #define AT_LOADK(kt) do { _Pragma("unroll") for (int i_ = 0; i_ < 2; ++i_) { const int id_ = tid + 512 * i_; \
;             kr[i_] = *(const u32x4*)(kbase + (size_t)((kt) * 64 + (id_ >> 4)) * 4096 + (id_ & 15) * 8); } } while (0)
; #define AT_LOADV(kt) do { _Pragma("unroll") for (int i_ = 0; i_ < 2; ++i_) { const int id_ = tid + 512 * i_; \
;             vr[i_] = *(const u32x4*)(vbase + (size_t)(id_ >> 3) * 4096 + (kt) * 64 + (id_ & 7) * 8); } } while (0)
; __device__ __forceinline__ void phase_attn(const Params& p, unsigned char* lds) {
;     ...
;         for (int kt = 0; kt < 64; ++kt) {
;             const int buf = kt & 1;
;             if (kt + 1 < 64) { AT_LOADK((kt + 1 + toff) & 63); AT_LOADV((kt + 1 + toff) & 63); }
;             AT_QK(st, buf);
;             float mloc = st[0][0];
; #pragma unroll
;             for (int i = 0; i < 16; ++i) { mloc = fmaxf(mloc, st[0][i]); mloc = fmaxf(mloc, st[1][i]); }
;             mloc = fmaxf(mloc, __shfl_xor(mloc, 32));
;             const float mnew = fmaxf(mrun, mloc);
;             if (__builtin_amdgcn_ballot_w64(mnew > mrun) != 0ull) {
;                 const float alpha = __builtin_amdgcn_exp2f(mrun - mnew);
;                 lsum *= alpha;
; #pragma unroll
;                 for (int vb = 0; vb < 4; ++vb)
; #pragma unroll
;                     for (int i = 0; i < 16; ++i) ot[vb][i] *= alpha;
;             }
.Lat_keepm_4:
	s_add_i32 s21, s21, 64
	s_add_i32 s20, s20, 1
	s_waitcnt lgkmcnt(0)
	s_barrier
	ds_read_b128 v[172:175], v157 offset:17408
	ds_read_b128 v[176:179], v157 offset:17440
	ds_read_b128 v[180:183], v157 offset:17472
	ds_read_b128 v[184:187], v157 offset:17504
	ds_read_b128 v[188:191], v157 offset:26112
	ds_read_b128 v[192:195], v157 offset:26144
	ds_read_b128 v[228:231], v157 offset:26176
	ds_read_b128 v[232:235], v157 offset:26208
	s_add_i32 s12, s21, 64
	s_and_b32 s12, s12, 0xfc0
	v_add_u32_e32 v116, s12, v162
	v_ashrrev_i32_e32 v117, 31, v116
	v_add_u32_e32 v112, s12, v163
	v_lshlrev_b64 v[116:117], 13, v[116:117]
	v_ashrrev_i32_e32 v113, 31, v112
	v_lshl_add_u64 v[116:117], v[152:153], 0, v[116:117]
	v_lshlrev_b64 v[112:113], 13, v[112:113]
	v_lshl_add_u64 v[112:113], v[152:153], 0, v[112:113]
	global_load_dwordx4 v[116:119], v[116:117], off
	global_load_dwordx4 v[112:115], v[112:113], off
	s_and_b32 s12, s21, 0xfc0
	s_lshl_b32 s12, s12, 1
	v_lshl_add_u64 v[124:125], v[154:155], 0, s[12:13]
	v_lshl_add_u64 v[120:121], v[124:125], 0, v[138:139]
	v_lshl_add_u64 v[124:125], v[124:125], 0, v[136:137]
	global_load_dwordx4 v[124:127], v[124:125], off
	global_load_dwordx4 v[120:123], v[120:121], off
	s_cbranch_vccz .Lat_norescale_5
	v_pk_mul_f32 v[62:63], v[62:63], v[238:239] op_sel_hi:[1,0]
	v_pk_mul_f32 v[60:61], v[60:61], v[238:239] op_sel_hi:[1,0]
	v_pk_mul_f32 v[58:59], v[58:59], v[238:239] op_sel_hi:[1,0]
	v_pk_mul_f32 v[56:57], v[56:57], v[238:239] op_sel_hi:[1,0]
	v_pk_mul_f32 v[54:55], v[54:55], v[238:239] op_sel_hi:[1,0]
	v_pk_mul_f32 v[52:53], v[52:53], v[238:239] op_sel_hi:[1,0]
	v_pk_mul_f32 v[50:51], v[50:51], v[238:239] op_sel_hi:[1,0]
	v_pk_mul_f32 v[48:49], v[48:49], v[238:239] op_sel_hi:[1,0]
	v_pk_mul_f32 v[46:47], v[46:47], v[238:239] op_sel_hi:[1,0]
	v_pk_mul_f32 v[44:45], v[44:45], v[238:239] op_sel_hi:[1,0]
	v_pk_mul_f32 v[42:43], v[42:43], v[238:239] op_sel_hi:[1,0]
	v_pk_mul_f32 v[40:41], v[40:41], v[238:239] op_sel_hi:[1,0]
	v_pk_mul_f32 v[38:39], v[38:39], v[238:239] op_sel_hi:[1,0]
	v_pk_mul_f32 v[36:37], v[36:37], v[238:239] op_sel_hi:[1,0]
	v_pk_mul_f32 v[34:35], v[34:35], v[238:239] op_sel_hi:[1,0]
	v_pk_mul_f32 v[32:33], v[32:33], v[238:239] op_sel_hi:[1,0]
	v_pk_mul_f32 v[30:31], v[30:31], v[238:239] op_sel_hi:[1,0]
	v_pk_mul_f32 v[28:29], v[28:29], v[238:239] op_sel_hi:[1,0]
	v_pk_mul_f32 v[26:27], v[26:27], v[238:239] op_sel_hi:[1,0]
	v_pk_mul_f32 v[24:25], v[24:25], v[238:239] op_sel_hi:[1,0]
	v_pk_mul_f32 v[22:23], v[22:23], v[238:239] op_sel_hi:[1,0]
	v_pk_mul_f32 v[20:21], v[20:21], v[238:239] op_sel_hi:[1,0]
	v_pk_mul_f32 v[18:19], v[18:19], v[238:239] op_sel_hi:[1,0]
	v_pk_mul_f32 v[16:17], v[16:17], v[238:239] op_sel_hi:[1,0]
	v_pk_mul_f32 v[14:15], v[14:15], v[238:239] op_sel_hi:[1,0]
	v_pk_mul_f32 v[12:13], v[12:13], v[238:239] op_sel_hi:[1,0]
	v_pk_mul_f32 v[10:11], v[10:11], v[238:239] op_sel_hi:[1,0]
	v_pk_mul_f32 v[8:9], v[8:9], v[238:239] op_sel_hi:[1,0]
	v_pk_mul_f32 v[6:7], v[6:7], v[238:239] op_sel_hi:[1,0]
	v_pk_mul_f32 v[4:5], v[4:5], v[238:239] op_sel_hi:[1,0]
	v_pk_mul_f32 v[2:3], v[2:3], v[238:239] op_sel_hi:[1,0]
	v_pk_mul_f32 v[0:1], v[0:1], v[238:239] op_sel_hi:[1,0]
	v_mul_f32_e32 v128, v128, v238

; __device__ __forceinline__ unsigned cvt_pk_bf16(float lo, float hi) { unsigned r; asm volatile("v_cvt_pk_bf16_f32 %0, %1, %2" : "=v"(r) : "v"(lo), "v"(hi)); return r; }
; #define AT_LDV(set, vb) do { _Pragma("unroll") for (int kb = 0; kb < 2; ++kb) _Pragma("unroll") for (int s2 = 0; s2 < 2; ++s2) \
;                     vf[set][kb * 2 + s2] = *(const bf16x8*)(sVt + buf * 9216 + (32 * (vb) + ql) * 72 + 32 * kb + 16 * s2 + 8 * g); } while (0)
; __device__ __forceinline__ void phase_attn(const Params& p, unsigned char* lds) {
;     ...
;             if (__builtin_amdgcn_ballot_w64(mnew > mrun) != 0ull) {
;                 const float alpha = __builtin_amdgcn_exp2f(mrun - mnew);
;                 lsum *= alpha;
; #pragma unroll
;                 for (int vb = 0; vb < 4; ++vb)
; #pragma unroll
;                     for (int i = 0; i < 16; ++i) ot[vb][i] *= alpha;
;             }
;             mrun = mnew;
;             bf16x8 P[2][2];
; #pragma unroll
;             for (int kb = 0; kb < 2; ++kb)
; #pragma unroll
;                 for (int s2 = 0; s2 < 2; ++s2) { u32x4 pk;
; #pragma unroll
;                     for (int jj = 0; jj < 4; ++jj) { const float p0 = __builtin_amdgcn_exp2f(st[kb][8 * s2 + 2 * jj] - mnew), p1 = __builtin_amdgcn_exp2f(st[kb][8 * s2 + 2 * jj + 1] - mnew); lsum += p0 + p1; pk[jj] = cvt_pk_bf16(p0, p1); }
;                     P[kb][s2] = __builtin_bit_cast(bf16x8, pk); }
;             {
;                 bf16x8 vf[2][4];
;     ...
;                 AT_LDV(0, 0);
; #pragma unroll
;                 for (int vb = 0; vb < 4; ++vb) {
;                     if (vb < 3) AT_LDV((vb + 1) & 1, vb + 1);
;                     __builtin_amdgcn_sched_barrier(0);
;                     __builtin_amdgcn_s_setprio(2);
; #pragma unroll
;                     for (int kb = 0; kb < 2; ++kb)
; #pragma unroll
;                         for (int s2 = 0; s2 < 2; ++s2) ot[vb] = __builtin_amdgcn_mfma_f32_32x32x16_bf16(vf[vb & 1][kb * 2 + s2], P[kb][s2], ot[vb], 0, 0, 0);
;                     __builtin_amdgcn_s_setprio(0);
;                     __builtin_amdgcn_sched_barrier(0);
;                 }
;     ...
;             }
.Lat_keepm_6:
	s_add_i32 s21, s21, 64
	s_add_i32 s20, s20, 1
	s_waitcnt lgkmcnt(0)
	s_barrier
	s_cmp_lt_u32 s20, 63
	s_cbranch_scc1 .Lat_loop
	s_cbranch_vccz .Lat_norescale_7
	v_pk_mul_f32 v[62:63], v[62:63], v[238:239] op_sel_hi:[1,0]
	v_pk_mul_f32 v[60:61], v[60:61], v[238:239] op_sel_hi:[1,0]
	v_pk_mul_f32 v[58:59], v[58:59], v[238:239] op_sel_hi:[1,0]
	v_pk_mul_f32 v[56:57], v[56:57], v[238:239] op_sel_hi:[1,0]
	v_pk_mul_f32 v[54:55], v[54:55], v[238:239] op_sel_hi:[1,0]
	v_pk_mul_f32 v[52:53], v[52:53], v[238:239] op_sel_hi:[1,0]
	v_pk_mul_f32 v[50:51], v[50:51], v[238:239] op_sel_hi:[1,0]
	v_pk_mul_f32 v[48:49], v[48:49], v[238:239] op_sel_hi:[1,0]
	v_pk_mul_f32 v[46:47], v[46:47], v[238:239] op_sel_hi:[1,0]
	v_pk_mul_f32 v[44:45], v[44:45], v[238:239] op_sel_hi:[1,0]
	v_pk_mul_f32 v[42:43], v[42:43], v[238:239] op_sel_hi:[1,0]
	v_pk_mul_f32 v[40:41], v[40:41], v[238:239] op_sel_hi:[1,0]
	v_pk_mul_f32 v[38:39], v[38:39], v[238:239] op_sel_hi:[1,0]
	v_pk_mul_f32 v[36:37], v[36:37], v[238:239] op_sel_hi:[1,0]
	v_pk_mul_f32 v[34:35], v[34:35], v[238:239] op_sel_hi:[1,0]
	v_pk_mul_f32 v[32:33], v[32:33], v[238:239] op_sel_hi:[1,0]
	v_pk_mul_f32 v[30:31], v[30:31], v[238:239] op_sel_hi:[1,0]
	v_pk_mul_f32 v[28:29], v[28:29], v[238:239] op_sel_hi:[1,0]
	v_pk_mul_f32 v[26:27], v[26:27], v[238:239] op_sel_hi:[1,0]
	v_pk_mul_f32 v[24:25], v[24:25], v[238:239] op_sel_hi:[1,0]
	v_pk_mul_f32 v[22:23], v[22:23], v[238:239] op_sel_hi:[1,0]
	v_pk_mul_f32 v[20:21], v[20:21], v[238:239] op_sel_hi:[1,0]
	v_pk_mul_f32 v[18:19], v[18:19], v[238:239] op_sel_hi:[1,0]
	v_pk_mul_f32 v[16:17], v[16:17], v[238:239] op_sel_hi:[1,0]
	v_pk_mul_f32 v[14:15], v[14:15], v[238:239] op_sel_hi:[1,0]
	v_pk_mul_f32 v[12:13], v[12:13], v[238:239] op_sel_hi:[1,0]
	v_pk_mul_f32 v[10:11], v[10:11], v[238:239] op_sel_hi:[1,0]
	v_pk_mul_f32 v[8:9], v[8:9], v[238:239] op_sel_hi:[1,0]
	v_pk_mul_f32 v[6:7], v[6:7], v[238:239] op_sel_hi:[1,0]
	v_pk_mul_f32 v[4:5], v[4:5], v[238:239] op_sel_hi:[1,0]
	v_pk_mul_f32 v[2:3], v[2:3], v[238:239] op_sel_hi:[1,0]
	v_pk_mul_f32 v[0:1], v[0:1], v[238:239] op_sel_hi:[1,0]
	v_mul_f32_e32 v128, v128, v238
.Lat_norescale_7:
	v_mov_b32_e32 v236, 0
	v_mov_b32_e32 v237, 0
	v_sub_f32_e32 v196, v196, v149
	v_sub_f32_e32 v197, v197, v149
	v_sub_f32_e32 v198, v198, v149
	v_sub_f32_e32 v199, v199, v149
	v_sub_f32_e32 v200, v200, v149
	v_sub_f32_e32 v201, v201, v149
	v_sub_f32_e32 v202, v202, v149
	v_sub_f32_e32 v203, v203, v149
	v_sub_f32_e32 v204, v204, v149
	v_sub_f32_e32 v205, v205, v149
	v_sub_f32_e32 v206, v206, v149
	v_sub_f32_e32 v207, v207, v149
	v_sub_f32_e32 v208, v208, v149
	v_sub_f32_e32 v209, v209, v149
	v_sub_f32_e32 v210, v210, v149
	v_sub_f32_e32 v211, v211, v149
	v_sub_f32_e32 v212, v212, v149
	v_sub_f32_e32 v213, v213, v149
	v_sub_f32_e32 v214, v214, v149
	v_sub_f32_e32 v215, v215, v149
	v_sub_f32_e32 v216, v216, v149
	v_sub_f32_e32 v217, v217, v149
	v_sub_f32_e32 v218, v218, v149
	v_sub_f32_e32 v219, v219, v149
	v_sub_f32_e32 v220, v220, v149
	v_sub_f32_e32 v221, v221, v149
	v_sub_f32_e32 v222, v222, v149
	v_sub_f32_e32 v223, v223, v149
	v_sub_f32_e32 v224, v224, v149
	v_sub_f32_e32 v225, v225, v149
	v_sub_f32_e32 v226, v226, v149
	v_sub_f32_e32 v227, v227, v149
	v_exp_f32_e32 v196, v196
	v_exp_f32_e32 v197, v197
	v_exp_f32_e32 v198, v198
	v_exp_f32_e32 v199, v199
	v_exp_f32_e32 v200, v200
	v_exp_f32_e32 v201, v201
	v_exp_f32_e32 v202, v202
	v_exp_f32_e32 v203, v203
	v_exp_f32_e32 v204, v204
	v_exp_f32_e32 v205, v205
	v_exp_f32_e32 v206, v206
	v_exp_f32_e32 v207, v207
	v_exp_f32_e32 v208, v208
	v_exp_f32_e32 v209, v209
	v_exp_f32_e32 v210, v210
	v_exp_f32_e32 v211, v211
	v_exp_f32_e32 v212, v212
	v_exp_f32_e32 v213, v213
	v_exp_f32_e32 v214, v214
	v_exp_f32_e32 v215, v215
	v_exp_f32_e32 v216, v216
	v_exp_f32_e32 v217, v217
	v_exp_f32_e32 v218, v218
	v_exp_f32_e32 v219, v219
	v_exp_f32_e32 v220, v220
	v_exp_f32_e32 v221, v221
	v_exp_f32_e32 v222, v222
	v_exp_f32_e32 v223, v223
	v_exp_f32_e32 v224, v224
	v_exp_f32_e32 v225, v225
	v_exp_f32_e32 v226, v226
	v_exp_f32_e32 v227, v227
	v_pk_add_f32 v[236:237], v[236:237], v[196:197]
	v_cvt_pk_bf16_f32 v196, v196, v197
	v_pk_add_f32 v[236:237], v[236:237], v[198:199]
	v_cvt_pk_bf16_f32 v197, v198, v199
	v_pk_add_f32 v[236:237], v[236:237], v[200:201]
	v_cvt_pk_bf16_f32 v198, v200, v201
	v_pk_add_f32 v[236:237], v[236:237], v[202:203]
	v_cvt_pk_bf16_f32 v199, v202, v203
	v_pk_add_f32 v[236:237], v[236:237], v[204:205]
	v_cvt_pk_bf16_f32 v200, v204, v205
	v_pk_add_f32 v[236:237], v[236:237], v[206:207]
	v_cvt_pk_bf16_f32 v201, v206, v207
	v_pk_add_f32 v[236:237], v[236:237], v[208:209]
	v_cvt_pk_bf16_f32 v202, v208, v209
	v_pk_add_f32 v[236:237], v[236:237], v[210:211]
	v_cvt_pk_bf16_f32 v203, v210, v211
	v_pk_add_f32 v[236:237], v[236:237], v[212:213]
	v_cvt_pk_bf16_f32 v212, v212, v213
	v_pk_add_f32 v[236:237], v[236:237], v[214:215]
	v_cvt_pk_bf16_f32 v213, v214, v215
	v_pk_add_f32 v[236:237], v[236:237], v[216:217]
	v_cvt_pk_bf16_f32 v214, v216, v217
	v_pk_add_f32 v[236:237], v[236:237], v[218:219]
	v_cvt_pk_bf16_f32 v215, v218, v219
	v_pk_add_f32 v[236:237], v[236:237], v[220:221]
	v_cvt_pk_bf16_f32 v216, v220, v221
	v_pk_add_f32 v[236:237], v[236:237], v[222:223]
	v_cvt_pk_bf16_f32 v217, v222, v223
	v_pk_add_f32 v[236:237], v[236:237], v[224:225]
	v_cvt_pk_bf16_f32 v218, v224, v225
	v_pk_add_f32 v[236:237], v[236:237], v[226:227]
	v_cvt_pk_bf16_f32 v219, v226, v227
	ds_read_b128 v[172:175], v147 offset:34816
	ds_read_b128 v[176:179], v147 offset:34848
	ds_read_b128 v[180:183], v147 offset:34880
	ds_read_b128 v[184:187], v147 offset:34912
	ds_read_b128 v[188:191], v147 offset:39424
	ds_read_b128 v[192:195], v147 offset:39456
	ds_read_b128 v[228:231], v147 offset:39488
	ds_read_b128 v[232:235], v147 offset:39520
	v_add_f32_e32 v128, v128, v236
	v_add_f32_e32 v128, v128, v237
	s_waitcnt lgkmcnt(7)
; #define AT_STOREK(buf) do { _Pragma("unroll") for (int i_ = 0; i_ < 2; ++i_) { const int id_ = tid + 512 * i_; \
;             *(u32x4*)(sKt + (buf) * 8704 + (id_ >> 4) * 136 + (id_ & 15) * 8) = kr[i_]; } } while (0)
; #define AT_STOREV(buf) do { _Pragma("unroll") for (int i_ = 0; i_ < 2; ++i_) { const int id_ = tid + 512 * i_; \
;             *(u32x4*)(sVt + (buf) * 9216 + (id_ >> 3) * 72 + (id_ & 7) * 8) = vr[i_]; } } while (0)
; #define AT_LDV(set, vb) do { _Pragma("unroll") for (int kb = 0; kb < 2; ++kb) _Pragma("unroll") for (int s2 = 0; s2 < 2; ++s2) \
;                     vf[set][kb * 2 + s2] = *(const bf16x8*)(sVt + buf * 9216 + (32 * (vb) + ql) * 72 + 32 * kb + 16 * s2 + 8 * g); } while (0)
; __device__ __forceinline__ void phase_attn(const Params& p, unsigned char* lds) {
;     ...
;                 for (int vb = 0; vb < 4; ++vb) {
;                     if (vb < 3) AT_LDV((vb + 1) & 1, vb + 1);
;                     __builtin_amdgcn_sched_barrier(0);
;                     __builtin_amdgcn_s_setprio(2);
; #pragma unroll
;                     for (int kb = 0; kb < 2; ++kb)
; #pragma unroll
;                         for (int s2 = 0; s2 < 2; ++s2) ot[vb] = __builtin_amdgcn_mfma_f32_32x32x16_bf16(vf[vb & 1][kb * 2 + s2], P[kb][s2], ot[vb], 0, 0, 0);
;                     __builtin_amdgcn_s_setprio(0);
;                     __builtin_amdgcn_sched_barrier(0);
;                 }
;     ...
;             }
;             if (kt + 1 < 64) { AT_STOREK(buf ^ 1); AT_STOREV(buf ^ 1); }
;             __syncthreads();
;         }
;     ...
;         lsum += __shfl_xor(lsum, 32);
;         const float inv = 1.0f / lsum;
;         if (cmap == 1) {
; #pragma unroll
;             for (int vb = 0; vb < 4; ++vb)
; #pragma unroll
;                 for (int i = 0; i < 16; ++i) ex[(vb * 16 + i) * 256 + qsub * 64 + lane] = ot[vb][i] * inv;
;         }
	v_mfma_f32_32x32x16_bf16 v[48:63], v[172:175], v[196:199], v[48:63]
	s_waitcnt lgkmcnt(6)
	v_mfma_f32_32x32x16_bf16 v[48:63], v[176:179], v[200:203], v[48:63]
	s_waitcnt lgkmcnt(5)
	v_mfma_f32_32x32x16_bf16 v[48:63], v[180:183], v[212:215], v[48:63]
	s_waitcnt lgkmcnt(4)
	v_mfma_f32_32x32x16_bf16 v[48:63], v[184:187], v[216:219], v[48:63]
	ds_read_b128 v[172:175], v147 offset:44032
	ds_read_b128 v[176:179], v147 offset:44064
	ds_read_b128 v[180:183], v147 offset:44096
	ds_read_b128 v[184:187], v147 offset:44128
	s_waitcnt lgkmcnt(7)
	v_mfma_f32_32x32x16_bf16 v[32:47], v[188:191], v[196:199], v[32:47]
	s_waitcnt lgkmcnt(6)
	v_mfma_f32_32x32x16_bf16 v[32:47], v[192:195], v[200:203], v[32:47]
	s_waitcnt lgkmcnt(5)
	v_mfma_f32_32x32x16_bf16 v[32:47], v[228:231], v[212:215], v[32:47]
	s_waitcnt lgkmcnt(4)
	v_mfma_f32_32x32x16_bf16 v[32:47], v[232:235], v[216:219], v[32:47]
	ds_read_b128 v[188:191], v147 offset:48640
	ds_read_b128 v[192:195], v147 offset:48672
	ds_read_b128 v[228:231], v147 offset:48704
	ds_read_b128 v[232:235], v147 offset:48736
	s_waitcnt lgkmcnt(7)
	v_mfma_f32_32x32x16_bf16 v[16:31], v[172:175], v[196:199], v[16:31]
	s_waitcnt lgkmcnt(6)
	v_mfma_f32_32x32x16_bf16 v[16:31], v[176:179], v[200:203], v[16:31]
	s_waitcnt lgkmcnt(5)
	v_mfma_f32_32x32x16_bf16 v[16:31], v[180:183], v[212:215], v[16:31]
	s_waitcnt lgkmcnt(4)
	v_mfma_f32_32x32x16_bf16 v[16:31], v[184:187], v[216:219], v[16:31]
	s_waitcnt lgkmcnt(3)
	v_mfma_f32_32x32x16_bf16 v[0:15], v[188:191], v[196:199], v[0:15]
	s_waitcnt lgkmcnt(2)
	v_mfma_f32_32x32x16_bf16 v[0:15], v[192:195], v[200:203], v[0:15]
	s_waitcnt lgkmcnt(1)
	v_mfma_f32_32x32x16_bf16 v[0:15], v[228:231], v[212:215], v[0:15]
	s_waitcnt lgkmcnt(0)
	v_mfma_f32_32x32x16_bf16 v[0:15], v[232:235], v[216:219], v[0:15]
	v_mov_b32_e32 v64, v128
	ds_bpermute_b32 v65, v158, v64
	s_waitcnt lgkmcnt(0)
	s_barrier
	v_add_f32_e32 v64, v64, v65
	v_rcp_f32_e32 v66, v64
	s_nop 0
	v_fma_f32 v68, -v64, v66, 1.0
	v_fma_f32 v65, v68, v66, v66
	v_div_fixup_f32 v64, v65, v64, 1.0
	s_and_saveexec_b64 s[20:21], s[4:5]
	s_cbranch_execz .LBB0_2029
	v_mul_f32_e32 v65, v48, v64
	v_mul_f32_e32 v66, v49, v64
	ds_write2st64_b32 v160, v65, v66 offset1:4
	v_mul_f32_e32 v65, v50, v64
	v_mul_f32_e32 v66, v51, v64
	ds_write2st64_b32 v160, v65, v66 offset0:8 offset1:12
	v_mul_f32_e32 v65, v52, v64
	v_mul_f32_e32 v66, v53, v64
	ds_write2st64_b32 v160, v65, v66 offset0:16 offset1:20
	v_mul_f32_e32 v65, v54, v64
	v_mul_f32_e32 v66, v55, v64
	ds_write2st64_b32 v160, v65, v66 offset0:24 offset1:28
	v_mul_f32_e32 v65, v56, v64
	v_mul_f32_e32 v66, v57, v64
	ds_write2st64_b32 v160, v65, v66 offset0:32 offset1:36
	v_mul_f32_e32 v65, v58, v64
	v_mul_f32_e32 v66, v59, v64
	ds_write2st64_b32 v160, v65, v66 offset0:40 offset1:44
	v_mul_f32_e32 v65, v60, v64
	v_mul_f32_e32 v66, v61, v64
	ds_write2st64_b32 v160, v65, v66 offset0:48 offset1:52
	v_mul_f32_e32 v65, v62, v64
	v_mul_f32_e32 v66, v63, v64
	ds_write2st64_b32 v160, v65, v66 offset0:56 offset1:60
	v_mul_f32_e32 v65, v32, v64
	v_mul_f32_e32 v66, v33, v64
	ds_write2st64_b32 v160, v65, v66 offset0:64 offset1:68
	v_mul_f32_e32 v65, v34, v64
	v_mul_f32_e32 v66, v35, v64
	ds_write2st64_b32 v160, v65, v66 offset0:72 offset1:76
	v_mul_f32_e32 v65, v36, v64
	v_mul_f32_e32 v66, v37, v64
	ds_write2st64_b32 v160, v65, v66 offset0:80 offset1:84
	v_mul_f32_e32 v65, v38, v64
	v_mul_f32_e32 v66, v39, v64
	ds_write2st64_b32 v160, v65, v66 offset0:88 offset1:92
	v_mul_f32_e32 v65, v40, v64
	v_mul_f32_e32 v66, v41, v64
	ds_write2st64_b32 v160, v65, v66 offset0:96 offset1:100
	v_mul_f32_e32 v65, v42, v64
	v_mul_f32_e32 v66, v43, v64
	ds_write2st64_b32 v160, v65, v66 offset0:104 offset1:108
	v_mul_f32_e32 v65, v44, v64
	v_mul_f32_e32 v66, v45, v64
	ds_write2st64_b32 v160, v65, v66 offset0:112 offset1:116
	v_mul_f32_e32 v65, v46, v64
	v_mul_f32_e32 v66, v47, v64
	ds_write2st64_b32 v160, v65, v66 offset0:120 offset1:124
	v_mul_f32_e32 v65, v16, v64
	v_mul_f32_e32 v66, v17, v64
	ds_write2st64_b32 v160, v65, v66 offset0:128 offset1:132
	v_mul_f32_e32 v65, v18, v64
	v_mul_f32_e32 v66, v19, v64
	ds_write2st64_b32 v160, v65, v66 offset0:136 offset1:140
	v_mul_f32_e32 v65, v20, v64
	v_mul_f32_e32 v66, v21, v64
	ds_write2st64_b32 v160, v65, v66 offset0:144 offset1:148
	v_mul_f32_e32 v65, v22, v64
	v_mul_f32_e32 v66, v23, v64
	ds_write2st64_b32 v160, v65, v66 offset0:152 offset1:156
	v_mul_f32_e32 v65, v24, v64
	v_mul_f32_e32 v66, v25, v64
	ds_write2st64_b32 v160, v65, v66 offset0:160 offset1:164
	v_mul_f32_e32 v65, v26, v64
	v_mul_f32_e32 v66, v27, v64
	ds_write2st64_b32 v160, v65, v66 offset0:168 offset1:172
	v_mul_f32_e32 v65, v28, v64
	v_mul_f32_e32 v66, v29, v64
	ds_write2st64_b32 v160, v65, v66 offset0:176 offset1:180
	v_mul_f32_e32 v65, v30, v64
	v_mul_f32_e32 v66, v31, v64
	ds_write2st64_b32 v160, v65, v66 offset0:184 offset1:188
	v_mul_f32_e32 v65, v0, v64
	v_mul_f32_e32 v66, v1, v64
	ds_write2st64_b32 v160, v65, v66 offset0:192 offset1:196
	v_mul_f32_e32 v65, v2, v64
	v_mul_f32_e32 v66, v3, v64
	ds_write2st64_b32 v160, v65, v66 offset0:200 offset1:204
	v_mul_f32_e32 v65, v4, v64
	v_mul_f32_e32 v66, v5, v64
	ds_write2st64_b32 v160, v65, v66 offset0:208 offset1:212
	v_mul_f32_e32 v65, v6, v64
	v_mul_f32_e32 v66, v7, v64
	ds_write2st64_b32 v160, v65, v66 offset0:216 offset1:220
	v_mul_f32_e32 v65, v8, v64
	v_mul_f32_e32 v66, v9, v64
	ds_write2st64_b32 v160, v65, v66 offset0:224 offset1:228
	v_mul_f32_e32 v65, v10, v64
	v_mul_f32_e32 v66, v11, v64
	ds_write2st64_b32 v160, v65, v66 offset0:232 offset1:236
	v_mul_f32_e32 v65, v12, v64
	v_mul_f32_e32 v66, v13, v64
	ds_write2st64_b32 v160, v65, v66 offset0:240 offset1:244
	v_mul_f32_e32 v65, v14, v64
	v_mul_f32_e32 v66, v15, v64
	ds_write2st64_b32 v160, v65, v66 offset0:248 offset1:252
